# v34 + LN1 expert weight reads double-buffered inside the selected-group block (next chunk's LDS reads issued before the current chunk's FMAs)
# speedup vs baseline: 1.0290x; 1.0111x over previous
.LBB0_552:
	s_add_i32 s23, s7, 1
	s_waitcnt vmcnt(0)
	v_mov_b64_e32 v[38:39], v[84:85]
	v_mov_b64_e32 v[32:33], v[92:93]
	v_mov_b64_e32 v[34:35], v[90:91]
	v_mov_b64_e32 v[36:37], v[88:89]
	v_mov_b32_e32 v0, s23
	v_min_u32_e32 v0, 15, v0
	v_mov_b32_e32 v1, 0
	v_lshl_add_u64 v[0:1], v[82:83], 0, v[0:1]
	v_lshlrev_b64 v[2:3], 12, v[0:1]
	v_lshlrev_b64 v[0:1], 11, v[0:1]
	v_lshl_add_u64 v[12:13], v[62:63], 0, v[2:3]
	v_lshl_add_u64 v[92:93], v[64:65], 0, v[0:1]
	global_load_dwordx4 v[0:3], v[12:13], off nt
	global_load_dwordx2 v[84:85], v[92:93], off nt
	global_load_dwordx4 v[4:7], v[12:13], off offset:1024 nt
	global_load_dwordx2 v[88:89], v[92:93], off offset:512 nt
	global_load_dwordx4 v[8:11], v[12:13], off offset:2048 nt
	global_load_dwordx2 v[90:91], v[92:93], off offset:1024 nt
	s_nop 0
	global_load_dwordx4 v[12:15], v[12:13], off offset:3072 nt
	s_nop 0
	global_load_dwordx2 v[92:93], v[92:93], off offset:1536 nt
	v_lshlrev_b32_e32 v40, 16, v38
	v_and_b32_e32 v41, 0xffff0000, v38
	v_lshlrev_b32_e32 v38, 16, v39
	v_and_b32_e32 v39, 0xffff0000, v39
	v_lshlrev_b32_e32 v54, 16, v36
	v_and_b32_e32 v55, 0xffff0000, v36
	v_lshlrev_b32_e32 v94, 16, v37
	v_and_b32_e32 v95, 0xffff0000, v37
	v_lshlrev_b32_e32 v96, 16, v34
	v_and_b32_e32 v97, 0xffff0000, v34
	v_lshlrev_b32_e32 v100, 16, v35
	v_and_b32_e32 v101, 0xffff0000, v35
	v_lshlrev_b32_e32 v102, 16, v32
	v_and_b32_e32 v103, 0xffff0000, v32
	v_lshlrev_b32_e32 v104, 16, v33
	v_and_b32_e32 v105, 0xffff0000, v33
	v_pk_fma_f32 v[106:107], v[30:31], s[22:23], v[38:39] op_sel_hi:[1,0,1]
	ds_read_b128 v[30:33], v234
	ds_read_b128 v[34:37], v234 offset:4096
	v_pk_fma_f32 v[28:29], v[28:29], s[22:23], v[40:41] op_sel_hi:[1,0,1]
	v_pk_fma_f32 v[20:21], v[20:21], s[22:23], v[54:55] op_sel_hi:[1,0,1]
	v_add_f32_e32 v38, v28, v29
	v_add_f32_e32 v38, v38, v106
	v_pk_fma_f32 v[22:23], v[22:23], s[22:23], v[94:95] op_sel_hi:[1,0,1]
	v_add_f32_e32 v54, v20, v21
	v_pk_fma_f32 v[24:25], v[24:25], s[22:23], v[96:97] op_sel_hi:[1,0,1]
	v_add_f32_e32 v38, v107, v38
	v_add_f32_e32 v54, v54, v22
	v_pk_fma_f32 v[26:27], v[26:27], s[22:23], v[100:101] op_sel_hi:[1,0,1]
	v_add_f32_e32 v55, v24, v25
	v_add_f32_e32 v98, 0, v38
	v_add_f32_e32 v54, v23, v54
	v_add_f32_e32 v55, v55, v26
	v_add_f32_e32 v54, v98, v54
	v_add_f32_e32 v55, v27, v55
	v_pk_fma_f32 v[16:17], v[16:17], s[22:23], v[102:103] op_sel_hi:[1,0,1]
	v_add_f32_e32 v54, v54, v55
	v_pk_fma_f32 v[18:19], v[18:19], s[22:23], v[104:105] op_sel_hi:[1,0,1]
	v_add_f32_e32 v55, v16, v17
	v_add_f32_e32 v55, v55, v18
	v_add_f32_e32 v55, v19, v55
	v_add_f32_e32 v54, v54, v55
	s_nop 1
	v_add_f32_dpp v54, v54, v54 quad_perm:[1,0,3,2] row_mask:0xf bank_mask:0xf bound_ctrl:1
	s_nop 1
	v_add_f32_dpp v54, v54, v54 quad_perm:[2,3,0,1] row_mask:0xf bank_mask:0xf bound_ctrl:1
	s_nop 1
	v_add_f32_dpp v54, v54, v54 row_half_mirror row_mask:0xf bank_mask:0xf bound_ctrl:1
	s_nop 1
	v_add_f32_dpp v54, v54, v54 row_mirror row_mask:0xf bank_mask:0xf bound_ctrl:1
	s_nop 0
	v_readlane_b32 s2, v54, 16
	v_readlane_b32 s4, v54, 48
	v_readlane_b32 s0, v54, 0
	v_readlane_b32 s1, v54, 32
	v_mov_b32_e32 v54, s2
	v_mov_b32_e32 v55, s4
	v_pk_add_f32 v[54:55], s[0:1], v[54:55]
	s_nop 0
	v_add_f32_e32 v54, v54, v55
	v_mul_f32_e32 v54, 0x3a800000, v54
	v_pk_add_f32 v[28:29], v[28:29], v[54:55] op_sel_hi:[1,0] neg_lo:[0,1] neg_hi:[0,1]
	v_pk_add_f32 v[126:127], v[106:107], v[54:55] op_sel_hi:[1,0] neg_lo:[0,1] neg_hi:[0,1]
	v_pk_mul_f32 v[104:105], v[28:29], v[28:29]
	v_pk_mul_f32 v[106:107], v[126:127], v[126:127]
	v_pk_add_f32 v[158:159], v[20:21], v[54:55] op_sel_hi:[1,0] neg_lo:[0,1] neg_hi:[0,1]
	v_pk_add_f32 v[160:161], v[22:23], v[54:55] op_sel_hi:[1,0] neg_lo:[0,1] neg_hi:[0,1]
	v_pk_add_f32 v[100:101], v[24:25], v[54:55] op_sel_hi:[1,0] neg_lo:[0,1] neg_hi:[0,1]
	v_pk_add_f32 v[102:103], v[26:27], v[54:55] op_sel_hi:[1,0] neg_lo:[0,1] neg_hi:[0,1]
	v_pk_add_f32 v[94:95], v[16:17], v[54:55] op_sel_hi:[1,0] neg_lo:[0,1] neg_hi:[0,1]
	v_pk_add_f32 v[96:97], v[18:19], v[54:55] op_sel_hi:[1,0] neg_lo:[0,1] neg_hi:[0,1]
	v_add_f32_e32 v54, v104, v105
	v_add_f32_e32 v54, v106, v54
	v_pk_mul_f32 v[20:21], v[158:159], v[158:159]
	v_add_f32_e32 v54, v107, v54
	v_add_f32_e32 v20, v20, v54
	v_pk_mul_f32 v[22:23], v[160:161], v[160:161]
	v_add_f32_e32 v20, v21, v20
	v_add_f32_e32 v20, v22, v20
	v_pk_mul_f32 v[24:25], v[100:101], v[100:101]
	v_add_f32_e32 v20, v23, v20
	v_add_f32_e32 v20, v24, v20
	v_pk_mul_f32 v[26:27], v[102:103], v[102:103]
	v_add_f32_e32 v20, v25, v20
	v_add_f32_e32 v20, v26, v20
	v_pk_mul_f32 v[16:17], v[94:95], v[94:95]
	v_add_f32_e32 v20, v27, v20
	v_add_f32_e32 v16, v16, v20
	v_pk_mul_f32 v[18:19], v[96:97], v[96:97]
	v_add_f32_e32 v16, v17, v16
	v_add_f32_e32 v16, v18, v16
	v_add_f32_e32 v16, v19, v16
	s_nop 1
	v_add_f32_dpp v16, v16, v16 quad_perm:[1,0,3,2] row_mask:0xf bank_mask:0xf bound_ctrl:1
	s_nop 1
	v_add_f32_dpp v16, v16, v16 quad_perm:[2,3,0,1] row_mask:0xf bank_mask:0xf bound_ctrl:1
	s_nop 1
	v_add_f32_dpp v16, v16, v16 row_half_mirror row_mask:0xf bank_mask:0xf bound_ctrl:1
	s_nop 1
	v_add_f32_dpp v16, v16, v16 row_mirror row_mask:0xf bank_mask:0xf bound_ctrl:1
	s_nop 0
	v_readlane_b32 s2, v16, 16
	v_readlane_b32 s4, v16, 48
	v_readlane_b32 s0, v16, 0
	v_readlane_b32 s1, v16, 32
	v_mov_b32_e32 v16, s2
	v_mov_b32_e32 v17, s4
	v_pk_add_f32 v[16:17], s[0:1], v[16:17]
	s_mov_b32 s0, 0x800000
	v_add_f32_e32 v16, v16, v17
	v_fmamk_f32 v16, v16, 0x3a800000, v116
	v_cmp_gt_f32_e32 vcc, s0, v16
	v_mul_f32_e32 v17, 0x4b800000, v16
	s_nop 0
	v_cndmask_b32_e32 v16, v16, v17, vcc
	v_rsq_f32_e32 v54, v16
	s_nop 0
	v_mul_f32_e32 v55, 0x45800000, v54
	v_cndmask_b32_e32 v98, v54, v55, vcc
	v_pk_mul_f32 v[28:29], v[28:29], v[98:99] op_sel_hi:[1,0]
	s_waitcnt lgkmcnt(0)
	v_pk_fma_f32 v[106:107], v[30:31], v[28:29], v[34:35]
	v_pk_mul_f32 v[28:29], v[126:127], v[98:99] op_sel_hi:[1,0]
	v_pk_fma_f32 v[104:105], v[32:33], v[28:29], v[36:37]
	v_cvt_pk_bf16_f32 v28, v106, v107
	v_cvt_pk_bf16_f32 v29, v104, v105
	v_mul_f32_e32 v252, v106, v183
	v_mul_f32_e32 v253, v106, v184
	v_mul_f32_e32 v254, v106, v182
	v_mul_f32_e32 v255, v106, v185
	v_fmac_f32_e32 v252, v107, v187
	v_fmac_f32_e32 v253, v107, v188
	v_fmac_f32_e32 v254, v107, v186
	v_fmac_f32_e32 v255, v107, v189
	v_fmac_f32_e32 v252, v104, v191
	v_fmac_f32_e32 v253, v104, v192
	v_fmac_f32_e32 v254, v104, v190
	v_fmac_f32_e32 v255, v104, v193
	v_fmac_f32_e32 v252, v105, v195
	v_fmac_f32_e32 v253, v105, v196
	v_fmac_f32_e32 v254, v105, v194
	v_fmac_f32_e32 v255, v105, v197
	global_store_dwordx2 v[86:87], v[28:29], off offset:-1024
	ds_read_b128 v[32:35], v234 offset:1024
	ds_read_b128 v[36:39], v234 offset:5120
	v_pk_mul_f32 v[40:41], v[158:159], v[98:99] op_sel_hi:[1,0]
	s_waitcnt lgkmcnt(0)
	v_pk_fma_f32 v[108:109], v[40:41], v[32:33], v[36:37]
	v_pk_mul_f32 v[32:33], v[160:161], v[98:99] op_sel_hi:[1,0]
	v_pk_fma_f32 v[110:111], v[32:33], v[34:35], v[38:39]
	v_cvt_pk_bf16_f32 v32, v108, v109
	v_cvt_pk_bf16_f32 v33, v110, v111
	v_fmac_f32_e32 v252, v108, v199
	v_fmac_f32_e32 v253, v108, v200
	v_fmac_f32_e32 v254, v108, v198
	v_fmac_f32_e32 v255, v108, v201
	v_fmac_f32_e32 v252, v109, v203
	v_fmac_f32_e32 v253, v109, v204
	v_fmac_f32_e32 v254, v109, v202
	v_fmac_f32_e32 v255, v109, v205
	v_fmac_f32_e32 v252, v110, v207
	v_fmac_f32_e32 v253, v110, v208
	v_fmac_f32_e32 v254, v110, v206
	v_fmac_f32_e32 v255, v110, v209
	v_fmac_f32_e32 v252, v111, v211
	v_fmac_f32_e32 v253, v111, v212
	v_fmac_f32_e32 v254, v111, v210
	v_fmac_f32_e32 v255, v111, v213
	global_store_dwordx2 v[86:87], v[32:33], off offset:-512
	ds_read_b128 v[48:51], v234 offset:2048
	ds_read_b128 v[52:55], v234 offset:6144
	v_pk_mul_f32 v[20:21], v[102:103], v[98:99] op_sel_hi:[1,0]
	s_waitcnt lgkmcnt(0)
	v_pk_fma_f32 v[50:51], v[20:21], v[50:51], v[54:55]
	v_pk_mul_f32 v[16:17], v[100:101], v[98:99] op_sel_hi:[1,0]
	v_cvt_pk_bf16_f32 v21, v50, v51
	v_pk_fma_f32 v[48:49], v[16:17], v[48:49], v[52:53]
	v_cvt_pk_bf16_f32 v20, v48, v49
	v_fmac_f32_e32 v252, v50, v223
	v_fmac_f32_e32 v253, v50, v224
	v_fmac_f32_e32 v254, v50, v222
	v_fmac_f32_e32 v255, v50, v225
	v_fmac_f32_e32 v252, v51, v227
	v_fmac_f32_e32 v253, v51, v228
	v_fmac_f32_e32 v254, v51, v226
	v_fmac_f32_e32 v255, v51, v229
	v_fmac_f32_e32 v252, v48, v215
	v_fmac_f32_e32 v253, v48, v216
	v_fmac_f32_e32 v254, v48, v214
	v_fmac_f32_e32 v255, v48, v217
	v_fmac_f32_e32 v252, v49, v219
	v_fmac_f32_e32 v253, v49, v220
	v_fmac_f32_e32 v254, v49, v218
	v_fmac_f32_e32 v255, v49, v221
	global_store_dwordx2 v[86:87], v[20:21], off
	v_pk_mul_f32 v[46:47], v[94:95], v[98:99] op_sel_hi:[1,0]
	ds_read_b128 v[32:35], v234 offset:3072
	ds_read_b128 v[36:39], v234 offset:7168
	s_waitcnt lgkmcnt(0)
	v_pk_fma_f32 v[52:53], v[46:47], v[32:33], v[36:37]
	v_pk_mul_f32 v[32:33], v[96:97], v[98:99] op_sel_hi:[1,0]
	v_pk_fma_f32 v[54:55], v[32:33], v[34:35], v[38:39]
	v_cvt_pk_bf16_f32 v32, v52, v53
	v_cvt_pk_bf16_f32 v33, v54, v55
	v_fmac_f32_e32 v252, v52, v231
	v_fmac_f32_e32 v253, v52, v232
	v_fmac_f32_e32 v254, v52, v230
	v_fmac_f32_e32 v255, v52, v233
	v_fmac_f32_e32 v252, v53, v239
	v_fmac_f32_e32 v253, v53, v240
	v_fmac_f32_e32 v254, v53, v238
	v_fmac_f32_e32 v255, v53, v241
	v_fmac_f32_e32 v252, v54, v243
	v_fmac_f32_e32 v253, v54, v244
	v_fmac_f32_e32 v254, v54, v242
	v_fmac_f32_e32 v255, v54, v245
	v_fmac_f32_e32 v252, v55, v247
	v_fmac_f32_e32 v253, v55, v248
	v_fmac_f32_e32 v254, v55, v246
	v_fmac_f32_e32 v255, v55, v249
	global_store_dwordx2 v[86:87], v[32:33], off offset:512
	v_add_f32_dpp v250, v252, v252 row_mirror row_mask:0xf bank_mask:0xf bound_ctrl:1
	v_add_f32_dpp v250, v253, v253 row_mirror row_mask:0xf bank_mask:0xc bound_ctrl:1
	v_add_f32_dpp v251, v254, v254 row_mirror row_mask:0xf bank_mask:0xf bound_ctrl:1
	v_add_f32_dpp v251, v255, v255 row_mirror row_mask:0xf bank_mask:0xc bound_ctrl:1
	v_add_f32_dpp v250, v250, v250 row_half_mirror row_mask:0xf bank_mask:0xf bound_ctrl:1
	s_nop 0
	v_add_f32_dpp v250, v251, v251 row_half_mirror row_mask:0xf bank_mask:0xa bound_ctrl:1
	s_nop 1
	v_add_f32_dpp v250, v250, v250 quad_perm:[1,0,3,2] row_mask:0xf bank_mask:0xf bound_ctrl:1
	s_nop 1
	v_add_f32_dpp v250, v250, v250 quad_perm:[2,3,0,1] row_mask:0xf bank_mask:0xf bound_ctrl:1
	s_nop 0
	v_readlane_b32 s2, v250, 20
	v_readlane_b32 s4, v250, 52
	v_readlane_b32 s0, v250, 4
	v_readlane_b32 s1, v250, 36
	v_mov_b32_e32 v16, s2
	v_mov_b32_e32 v17, s4
	v_readlane_b32 s2, v250, 16
	v_readlane_b32 s4, v250, 48
	v_pk_add_f32 v[16:17], s[0:1], v[16:17]
	v_readlane_b32 s0, v250, 0
	v_readlane_b32 s1, v250, 32
	v_mov_b32_e32 v18, s2
	v_mov_b32_e32 v19, s4
	v_readlane_b32 s2, v250, 24
	v_readlane_b32 s4, v250, 56
	v_pk_add_f32 v[18:19], s[0:1], v[18:19]
	v_readlane_b32 s0, v250, 8
	v_readlane_b32 s1, v250, 40
	v_mov_b32_e32 v20, s2
	v_mov_b32_e32 v21, s4
	v_pk_add_f32 v[20:21], s[0:1], v[20:21]
	v_mov_b32_e32 v25, v18
	v_add_f32_e32 v26, v20, v21
	v_mov_b32_e32 v18, v17
	v_readlane_b32 s2, v250, 28
	v_readlane_b32 s4, v250, 60
	v_readlane_b32 s0, v250, 12
	v_readlane_b32 s1, v250, 44
	v_mov_b32_e32 v20, s2
	v_mov_b32_e32 v21, s4
	v_pk_add_f32 v[20:21], s[0:1], v[20:21]
	v_add_f32_e32 v27, v20, v21
	v_mov_b32_e32 v24, v16
	v_pk_add_f32 v[16:17], v[24:25], v[18:19]
	v_mov_b32_e32 v20, v178
	v_mov_b32_e32 v21, v179
	v_mov_b32_e32 v22, v180
	v_mov_b32_e32 v23, v181
	v_add_f32_e32 v19, v26, v22
	v_pk_add_f32 v[16:17], v[16:17], v[20:21]
	v_add_f32_e32 v18, v27, v23
	v_cmp_gt_f32_e32 vcc, v17, v16
	s_nop 0
	s_nop 0
	v_cndmask_b32_e32 v20, v16, v17, vcc
	v_cmp_gt_f32_e64 s[18:19], v19, v20
	v_cndmask_b32_e64 v21, 0, 1, vcc
	s_and_b64 s[14:15], s[18:19], exec
	v_cndmask_b32_e64 v20, v20, v19, s[18:19]
	v_cmp_ngt_f32_e64 s[0:1], v18, v20
	v_readfirstlane_b32 s2, v21
	s_cselect_b32 s2, 2, s2
	s_and_b64 s[14:15], s[0:1], exec
	s_cselect_b32 s2, s2, 3
	s_cmp_eq_u32 s2, 0
	s_waitcnt lgkmcnt(0)
	s_cbranch_scc0 .Lmy_rsela_1
	ds_read_b128 v[146:149], v60
	ds_read_b128 v[150:153], v60 offset:4096
	ds_read_b128 v[154:157], v60 offset:8192
	ds_read_b128 v[66:69], v60 offset:12288
	ds_read_b128 v[130:133], v60 offset:1024
	ds_read_b128 v[134:137], v60 offset:5120
	ds_read_b128 v[138:141], v60 offset:9216
	ds_read_b128 v[142:145], v60 offset:13312
	s_waitcnt lgkmcnt(7)
	v_mul_f32_e32 v252, v106, v146
	v_fmac_f32_e32 v252, v107, v147
	v_fmac_f32_e32 v252, v104, v148
	v_fmac_f32_e32 v252, v105, v149
	s_waitcnt lgkmcnt(6)
	v_mul_f32_e32 v253, v106, v150
	v_fmac_f32_e32 v253, v107, v151
	v_fmac_f32_e32 v253, v104, v152
	v_fmac_f32_e32 v253, v105, v153
	s_waitcnt lgkmcnt(5)
	v_mul_f32_e32 v254, v106, v154
	v_fmac_f32_e32 v254, v107, v155
	v_fmac_f32_e32 v254, v104, v156
	v_fmac_f32_e32 v254, v105, v157
	s_waitcnt lgkmcnt(4)
	v_mul_f32_e32 v255, v106, v66
	v_fmac_f32_e32 v255, v107, v67
	v_fmac_f32_e32 v255, v104, v68
	v_fmac_f32_e32 v255, v105, v69
	ds_read_b128 v[146:149], v60 offset:2048
	ds_read_b128 v[150:153], v60 offset:6144
	ds_read_b128 v[154:157], v60 offset:10240
	ds_read_b128 v[66:69], v60 offset:14336
	s_waitcnt lgkmcnt(7)
	v_fmac_f32_e32 v252, v108, v130
	v_fmac_f32_e32 v252, v109, v131
	v_fmac_f32_e32 v252, v110, v132
	v_fmac_f32_e32 v252, v111, v133
	s_waitcnt lgkmcnt(6)
	v_fmac_f32_e32 v253, v108, v134
	v_fmac_f32_e32 v253, v109, v135
	v_fmac_f32_e32 v253, v110, v136
	v_fmac_f32_e32 v253, v111, v137
	s_waitcnt lgkmcnt(5)
	v_fmac_f32_e32 v254, v108, v138
	v_fmac_f32_e32 v254, v109, v139
	v_fmac_f32_e32 v254, v110, v140
	v_fmac_f32_e32 v254, v111, v141
	s_waitcnt lgkmcnt(4)
	v_fmac_f32_e32 v255, v108, v142
	v_fmac_f32_e32 v255, v109, v143
	v_fmac_f32_e32 v255, v110, v144
	v_fmac_f32_e32 v255, v111, v145
	ds_read_b128 v[130:133], v60 offset:3072
	ds_read_b128 v[134:137], v60 offset:7168
	ds_read_b128 v[138:141], v60 offset:11264
	ds_read_b128 v[142:145], v60 offset:15360
	s_waitcnt lgkmcnt(7)
	v_fmac_f32_e32 v252, v50, v148
	v_fmac_f32_e32 v252, v51, v149
	v_fmac_f32_e32 v252, v48, v146
	v_fmac_f32_e32 v252, v49, v147
	s_waitcnt lgkmcnt(6)
	v_fmac_f32_e32 v253, v50, v152
	v_fmac_f32_e32 v253, v51, v153
	v_fmac_f32_e32 v253, v48, v150
	v_fmac_f32_e32 v253, v49, v151
	s_waitcnt lgkmcnt(5)
	v_fmac_f32_e32 v254, v50, v156
	v_fmac_f32_e32 v254, v51, v157
	v_fmac_f32_e32 v254, v48, v154
	v_fmac_f32_e32 v254, v49, v155
	s_waitcnt lgkmcnt(4)
	v_fmac_f32_e32 v255, v50, v68
	v_fmac_f32_e32 v255, v51, v69
	v_fmac_f32_e32 v255, v48, v66
	v_fmac_f32_e32 v255, v49, v67
	s_waitcnt lgkmcnt(3)
	v_fmac_f32_e32 v252, v52, v130
	v_fmac_f32_e32 v252, v53, v131
	v_fmac_f32_e32 v252, v54, v132
	v_fmac_f32_e32 v252, v55, v133
	s_waitcnt lgkmcnt(2)
	v_fmac_f32_e32 v253, v52, v134
	v_fmac_f32_e32 v253, v53, v135
	v_fmac_f32_e32 v253, v54, v136
	v_fmac_f32_e32 v253, v55, v137
	s_waitcnt lgkmcnt(1)
	v_fmac_f32_e32 v254, v52, v138
	v_fmac_f32_e32 v254, v53, v139
	v_fmac_f32_e32 v254, v54, v140
	v_fmac_f32_e32 v254, v55, v141
	s_waitcnt lgkmcnt(0)
	v_fmac_f32_e32 v255, v52, v142
	v_fmac_f32_e32 v255, v53, v143
	v_fmac_f32_e32 v255, v54, v144
	v_fmac_f32_e32 v255, v55, v145
	v_add_f32_dpp v94, v252, v252 row_mirror row_mask:0xf bank_mask:0xf bound_ctrl:1
	v_add_f32_dpp v94, v253, v253 row_mirror row_mask:0xf bank_mask:0xc bound_ctrl:1
	v_add_f32_dpp v96, v254, v254 row_mirror row_mask:0xf bank_mask:0xf bound_ctrl:1
	v_add_f32_dpp v96, v255, v255 row_mirror row_mask:0xf bank_mask:0xc bound_ctrl:1
	v_add_f32_dpp v94, v94, v94 row_half_mirror row_mask:0xf bank_mask:0xf bound_ctrl:1
	s_nop 0
	v_add_f32_dpp v94, v96, v96 row_half_mirror row_mask:0xf bank_mask:0xa bound_ctrl:1
	s_nop 1
	v_add_f32_dpp v94, v94, v94 quad_perm:[1,0,3,2] row_mask:0xf bank_mask:0xf bound_ctrl:1
	s_nop 1
	v_add_f32_dpp v94, v94, v94 quad_perm:[2,3,0,1] row_mask:0xf bank_mask:0xf bound_ctrl:1
	s_nop 0
	v_readlane_b32 s20, v94, 0
	v_readlane_b32 s4, v94, 16
	v_readlane_b32 s21, v94, 32
	v_readlane_b32 s5, v94, 48
	v_readlane_b32 s91, v94, 8
	v_readlane_b32 s95, v94, 24
	v_readlane_b32 s94, v94, 40
	v_readlane_b32 s92, v94, 56
	v_readlane_b32 s6, v94, 4
	v_readlane_b32 s75, v94, 20
	v_readlane_b32 s74, v94, 36
	v_readlane_b32 s84, v94, 52
	v_readlane_b32 s97, v94, 12
	v_readlane_b32 s9, v94, 28
	v_readlane_b32 s8, v94, 44
	v_readlane_b32 s12, v94, 60
	s_branch .Lmy_rsela_end
.Lmy_rsela_1:
	s_cmp_eq_u32 s2, 1
	s_cbranch_scc0 .Lmy_rsela_2
	ds_read_b128 v[146:149], v60 offset:16384
	ds_read_b128 v[150:153], v60 offset:20480
	ds_read_b128 v[154:157], v60 offset:24576
	ds_read_b128 v[66:69], v60 offset:28672
	ds_read_b128 v[130:133], v60 offset:17408
	ds_read_b128 v[134:137], v60 offset:21504
	ds_read_b128 v[138:141], v60 offset:25600
	ds_read_b128 v[142:145], v60 offset:29696
	s_waitcnt lgkmcnt(7)
	v_mul_f32_e32 v252, v106, v146
	v_fmac_f32_e32 v252, v107, v147
	v_fmac_f32_e32 v252, v104, v148
	v_fmac_f32_e32 v252, v105, v149
	s_waitcnt lgkmcnt(6)
	v_mul_f32_e32 v253, v106, v150
	v_fmac_f32_e32 v253, v107, v151
	v_fmac_f32_e32 v253, v104, v152
	v_fmac_f32_e32 v253, v105, v153
	s_waitcnt lgkmcnt(5)
	v_mul_f32_e32 v254, v106, v154
	v_fmac_f32_e32 v254, v107, v155
	v_fmac_f32_e32 v254, v104, v156
	v_fmac_f32_e32 v254, v105, v157
	s_waitcnt lgkmcnt(4)
	v_mul_f32_e32 v255, v106, v66
	v_fmac_f32_e32 v255, v107, v67
	v_fmac_f32_e32 v255, v104, v68
	v_fmac_f32_e32 v255, v105, v69
	ds_read_b128 v[146:149], v60 offset:18432
	ds_read_b128 v[150:153], v60 offset:22528
	ds_read_b128 v[154:157], v60 offset:26624
	ds_read_b128 v[66:69], v60 offset:30720
	s_waitcnt lgkmcnt(7)
	v_fmac_f32_e32 v252, v108, v130
	v_fmac_f32_e32 v252, v109, v131
	v_fmac_f32_e32 v252, v110, v132
	v_fmac_f32_e32 v252, v111, v133
	s_waitcnt lgkmcnt(6)
	v_fmac_f32_e32 v253, v108, v134
	v_fmac_f32_e32 v253, v109, v135
	v_fmac_f32_e32 v253, v110, v136
	v_fmac_f32_e32 v253, v111, v137
	s_waitcnt lgkmcnt(5)
	v_fmac_f32_e32 v254, v108, v138
	v_fmac_f32_e32 v254, v109, v139
	v_fmac_f32_e32 v254, v110, v140
	v_fmac_f32_e32 v254, v111, v141
	s_waitcnt lgkmcnt(4)
	v_fmac_f32_e32 v255, v108, v142
	v_fmac_f32_e32 v255, v109, v143
	v_fmac_f32_e32 v255, v110, v144
	v_fmac_f32_e32 v255, v111, v145
	ds_read_b128 v[130:133], v60 offset:19456
	ds_read_b128 v[134:137], v60 offset:23552
	ds_read_b128 v[138:141], v60 offset:27648
	ds_read_b128 v[142:145], v60 offset:31744
	s_waitcnt lgkmcnt(7)
	v_fmac_f32_e32 v252, v50, v148
	v_fmac_f32_e32 v252, v51, v149
	v_fmac_f32_e32 v252, v48, v146
	v_fmac_f32_e32 v252, v49, v147
	s_waitcnt lgkmcnt(6)
	v_fmac_f32_e32 v253, v50, v152
	v_fmac_f32_e32 v253, v51, v153
	v_fmac_f32_e32 v253, v48, v150
	v_fmac_f32_e32 v253, v49, v151
	s_waitcnt lgkmcnt(5)
	v_fmac_f32_e32 v254, v50, v156
	v_fmac_f32_e32 v254, v51, v157
	v_fmac_f32_e32 v254, v48, v154
	v_fmac_f32_e32 v254, v49, v155
	s_waitcnt lgkmcnt(4)
	v_fmac_f32_e32 v255, v50, v68
	v_fmac_f32_e32 v255, v51, v69
	v_fmac_f32_e32 v255, v48, v66
	v_fmac_f32_e32 v255, v49, v67
	s_waitcnt lgkmcnt(3)
	v_fmac_f32_e32 v252, v52, v130
	v_fmac_f32_e32 v252, v53, v131
	v_fmac_f32_e32 v252, v54, v132
	v_fmac_f32_e32 v252, v55, v133
	s_waitcnt lgkmcnt(2)
	v_fmac_f32_e32 v253, v52, v134
	v_fmac_f32_e32 v253, v53, v135
	v_fmac_f32_e32 v253, v54, v136
	v_fmac_f32_e32 v253, v55, v137
	s_waitcnt lgkmcnt(1)
	v_fmac_f32_e32 v254, v52, v138
	v_fmac_f32_e32 v254, v53, v139
	v_fmac_f32_e32 v254, v54, v140
	v_fmac_f32_e32 v254, v55, v141
	s_waitcnt lgkmcnt(0)
	v_fmac_f32_e32 v255, v52, v142
	v_fmac_f32_e32 v255, v53, v143
	v_fmac_f32_e32 v255, v54, v144
	v_fmac_f32_e32 v255, v55, v145
	v_add_f32_dpp v125, v252, v252 row_mirror row_mask:0xf bank_mask:0xf bound_ctrl:1
	v_add_f32_dpp v125, v253, v253 row_mirror row_mask:0xf bank_mask:0xc bound_ctrl:1
	v_add_f32_dpp v98, v254, v254 row_mirror row_mask:0xf bank_mask:0xf bound_ctrl:1
	v_add_f32_dpp v98, v255, v255 row_mirror row_mask:0xf bank_mask:0xc bound_ctrl:1
	v_add_f32_dpp v125, v125, v125 row_half_mirror row_mask:0xf bank_mask:0xf bound_ctrl:1
	s_nop 0
	v_add_f32_dpp v125, v98, v98 row_half_mirror row_mask:0xf bank_mask:0xa bound_ctrl:1
	s_nop 1
	v_add_f32_dpp v125, v125, v125 quad_perm:[1,0,3,2] row_mask:0xf bank_mask:0xf bound_ctrl:1
	s_nop 1
	v_add_f32_dpp v125, v125, v125 quad_perm:[2,3,0,1] row_mask:0xf bank_mask:0xf bound_ctrl:1
	s_nop 0
	v_readlane_b32 s59, v125, 0
	v_readlane_b32 s61, v125, 16
	v_readlane_b32 s60, v125, 32
	v_readlane_b32 s82, v125, 48
	v_readlane_b32 s52, v125, 8
	v_readlane_b32 s54, v125, 24
	v_readlane_b32 s53, v125, 40
	v_readlane_b32 s93, v125, 56
	v_readlane_b32 s85, v125, 4
	v_readlane_b32 s87, v125, 20
	v_readlane_b32 s86, v125, 36
	v_readlane_b32 s90, v125, 52
	v_readlane_b32 s13, v125, 12
	v_readlane_b32 s24, v125, 28
	v_readlane_b32 s16, v125, 44
	v_readlane_b32 s17, v125, 60
	s_branch .Lmy_rsela_end
.Lmy_rsela_2:
	s_cmp_eq_u32 s2, 2
	s_cbranch_scc0 .Lmy_rsela_3
	ds_read_b128 v[146:149], v60 offset:32768
	ds_read_b128 v[150:153], v60 offset:36864
	ds_read_b128 v[154:157], v60 offset:40960
	ds_read_b128 v[66:69], v60 offset:45056
	ds_read_b128 v[130:133], v60 offset:33792
	ds_read_b128 v[134:137], v60 offset:37888
	ds_read_b128 v[138:141], v60 offset:41984
	ds_read_b128 v[142:145], v60 offset:46080
	s_waitcnt lgkmcnt(7)
	v_mul_f32_e32 v252, v106, v146
	v_fmac_f32_e32 v252, v107, v147
	v_fmac_f32_e32 v252, v104, v148
	v_fmac_f32_e32 v252, v105, v149
	s_waitcnt lgkmcnt(6)
	v_mul_f32_e32 v253, v106, v150
	v_fmac_f32_e32 v253, v107, v151
	v_fmac_f32_e32 v253, v104, v152
	v_fmac_f32_e32 v253, v105, v153
	s_waitcnt lgkmcnt(5)
	v_mul_f32_e32 v254, v106, v154
	v_fmac_f32_e32 v254, v107, v155
	v_fmac_f32_e32 v254, v104, v156
	v_fmac_f32_e32 v254, v105, v157
	s_waitcnt lgkmcnt(4)
	v_mul_f32_e32 v255, v106, v66
	v_fmac_f32_e32 v255, v107, v67
	v_fmac_f32_e32 v255, v104, v68
	v_fmac_f32_e32 v255, v105, v69
	ds_read_b128 v[146:149], v60 offset:34816
	ds_read_b128 v[150:153], v60 offset:38912
	ds_read_b128 v[154:157], v60 offset:43008
	ds_read_b128 v[66:69], v60 offset:47104
	s_waitcnt lgkmcnt(7)
	v_fmac_f32_e32 v252, v108, v130
	v_fmac_f32_e32 v252, v109, v131
	v_fmac_f32_e32 v252, v110, v132
	v_fmac_f32_e32 v252, v111, v133
	s_waitcnt lgkmcnt(6)
	v_fmac_f32_e32 v253, v108, v134
	v_fmac_f32_e32 v253, v109, v135
	v_fmac_f32_e32 v253, v110, v136
	v_fmac_f32_e32 v253, v111, v137
	s_waitcnt lgkmcnt(5)
	v_fmac_f32_e32 v254, v108, v138
	v_fmac_f32_e32 v254, v109, v139
	v_fmac_f32_e32 v254, v110, v140
	v_fmac_f32_e32 v254, v111, v141
	s_waitcnt lgkmcnt(4)
	v_fmac_f32_e32 v255, v108, v142
	v_fmac_f32_e32 v255, v109, v143
	v_fmac_f32_e32 v255, v110, v144
	v_fmac_f32_e32 v255, v111, v145
	ds_read_b128 v[130:133], v60 offset:35840
	ds_read_b128 v[134:137], v60 offset:39936
	ds_read_b128 v[138:141], v60 offset:44032
	ds_read_b128 v[142:145], v60 offset:48128
	s_waitcnt lgkmcnt(7)
	v_fmac_f32_e32 v252, v50, v148
	v_fmac_f32_e32 v252, v51, v149
	v_fmac_f32_e32 v252, v48, v146
	v_fmac_f32_e32 v252, v49, v147
	s_waitcnt lgkmcnt(6)
	v_fmac_f32_e32 v253, v50, v152
	v_fmac_f32_e32 v253, v51, v153
	v_fmac_f32_e32 v253, v48, v150
	v_fmac_f32_e32 v253, v49, v151
	s_waitcnt lgkmcnt(5)
	v_fmac_f32_e32 v254, v50, v156
	v_fmac_f32_e32 v254, v51, v157
	v_fmac_f32_e32 v254, v48, v154
	v_fmac_f32_e32 v254, v49, v155
	s_waitcnt lgkmcnt(4)
	v_fmac_f32_e32 v255, v50, v68
	v_fmac_f32_e32 v255, v51, v69
	v_fmac_f32_e32 v255, v48, v66
	v_fmac_f32_e32 v255, v49, v67
	s_waitcnt lgkmcnt(3)
	v_fmac_f32_e32 v252, v52, v130
	v_fmac_f32_e32 v252, v53, v131
	v_fmac_f32_e32 v252, v54, v132
	v_fmac_f32_e32 v252, v55, v133
	s_waitcnt lgkmcnt(2)
	v_fmac_f32_e32 v253, v52, v134
	v_fmac_f32_e32 v253, v53, v135
	v_fmac_f32_e32 v253, v54, v136
	v_fmac_f32_e32 v253, v55, v137
	s_waitcnt lgkmcnt(1)
	v_fmac_f32_e32 v254, v52, v138
	v_fmac_f32_e32 v254, v53, v139
	v_fmac_f32_e32 v254, v54, v140
	v_fmac_f32_e32 v254, v55, v141
	s_waitcnt lgkmcnt(0)
	v_fmac_f32_e32 v255, v52, v142
	v_fmac_f32_e32 v255, v53, v143
	v_fmac_f32_e32 v255, v54, v144
	v_fmac_f32_e32 v255, v55, v145
	v_add_f32_dpp v111, v252, v252 row_mirror row_mask:0xf bank_mask:0xf bound_ctrl:1
	v_add_f32_dpp v111, v253, v253 row_mirror row_mask:0xf bank_mask:0xc bound_ctrl:1
	v_add_f32_dpp v109, v254, v254 row_mirror row_mask:0xf bank_mask:0xf bound_ctrl:1
	v_add_f32_dpp v109, v255, v255 row_mirror row_mask:0xf bank_mask:0xc bound_ctrl:1
	v_add_f32_dpp v111, v111, v111 row_half_mirror row_mask:0xf bank_mask:0xf bound_ctrl:1
	s_nop 0
	v_add_f32_dpp v111, v109, v109 row_half_mirror row_mask:0xf bank_mask:0xa bound_ctrl:1
	s_nop 1
	v_add_f32_dpp v111, v111, v111 quad_perm:[1,0,3,2] row_mask:0xf bank_mask:0xf bound_ctrl:1
	s_nop 1
	v_add_f32_dpp v111, v111, v111 quad_perm:[2,3,0,1] row_mask:0xf bank_mask:0xf bound_ctrl:1
	s_nop 0
	v_readlane_b32 s83, v111, 0
	v_readlane_b32 s89, v111, 16
	v_readlane_b32 s88, v111, 32
	v_readlane_b32 s96, v111, 48
	v_readlane_b32 s55, v111, 8
	v_readlane_b32 s57, v111, 24
	v_readlane_b32 s56, v111, 40
	v_readlane_b32 s58, v111, 56
	v_readlane_b32 s46, v111, 4
	v_readlane_b32 s48, v111, 20
	v_readlane_b32 s47, v111, 36
	v_readlane_b32 s49, v111, 52
	v_readlane_b32 s38, v111, 12
	v_readlane_b32 s40, v111, 28
	v_readlane_b32 s39, v111, 44
	v_readlane_b32 s41, v111, 60
	s_branch .Lmy_rsela_end
.Lmy_rsela_3:
	ds_read_b128 v[146:149], v60 offset:49152
	ds_read_b128 v[150:153], v60 offset:53248
	ds_read_b128 v[154:157], v60 offset:57344
	ds_read_b128 v[66:69], v60 offset:61440
	ds_read_b128 v[130:133], v60 offset:50176
	ds_read_b128 v[134:137], v60 offset:54272
	ds_read_b128 v[138:141], v60 offset:58368
	ds_read_b128 v[142:145], v60 offset:62464
	s_waitcnt lgkmcnt(7)
	v_mul_f32_e32 v252, v106, v146
	v_fmac_f32_e32 v252, v107, v147
	v_fmac_f32_e32 v252, v104, v148
	v_fmac_f32_e32 v252, v105, v149
	s_waitcnt lgkmcnt(6)
	v_mul_f32_e32 v253, v106, v150
	v_fmac_f32_e32 v253, v107, v151
	v_fmac_f32_e32 v253, v104, v152
	v_fmac_f32_e32 v253, v105, v153
	s_waitcnt lgkmcnt(5)
	v_mul_f32_e32 v254, v106, v154
	v_fmac_f32_e32 v254, v107, v155
	v_fmac_f32_e32 v254, v104, v156
	v_fmac_f32_e32 v254, v105, v157
	s_waitcnt lgkmcnt(4)
	v_mul_f32_e32 v255, v106, v66
	v_fmac_f32_e32 v255, v107, v67
	v_fmac_f32_e32 v255, v104, v68
	v_fmac_f32_e32 v255, v105, v69
	ds_read_b128 v[146:149], v60 offset:51200
	ds_read_b128 v[150:153], v60 offset:55296
	ds_read_b128 v[154:157], v60 offset:59392
	ds_read_b128 v[66:69], v60 offset:63488
	s_waitcnt lgkmcnt(7)
	v_fmac_f32_e32 v252, v108, v130
	v_fmac_f32_e32 v252, v109, v131
	v_fmac_f32_e32 v252, v110, v132
	v_fmac_f32_e32 v252, v111, v133
	s_waitcnt lgkmcnt(6)
	v_fmac_f32_e32 v253, v108, v134
	v_fmac_f32_e32 v253, v109, v135
	v_fmac_f32_e32 v253, v110, v136
	v_fmac_f32_e32 v253, v111, v137
	s_waitcnt lgkmcnt(5)
	v_fmac_f32_e32 v254, v108, v138
	v_fmac_f32_e32 v254, v109, v139
	v_fmac_f32_e32 v254, v110, v140
	v_fmac_f32_e32 v254, v111, v141
	s_waitcnt lgkmcnt(4)
	v_fmac_f32_e32 v255, v108, v142
	v_fmac_f32_e32 v255, v109, v143
	v_fmac_f32_e32 v255, v110, v144
	v_fmac_f32_e32 v255, v111, v145
	ds_read_b128 v[130:133], v60 offset:52224
	ds_read_b128 v[134:137], v60 offset:56320
	ds_read_b128 v[138:141], v60 offset:60416
	ds_read_b128 v[142:145], v60 offset:64512
	s_waitcnt lgkmcnt(7)
	v_fmac_f32_e32 v252, v50, v148
	v_fmac_f32_e32 v252, v51, v149
	v_fmac_f32_e32 v252, v48, v146
	v_fmac_f32_e32 v252, v49, v147
	s_waitcnt lgkmcnt(6)
	v_fmac_f32_e32 v253, v50, v152
	v_fmac_f32_e32 v253, v51, v153
	v_fmac_f32_e32 v253, v48, v150
	v_fmac_f32_e32 v253, v49, v151
	s_waitcnt lgkmcnt(5)
	v_fmac_f32_e32 v254, v50, v156
	v_fmac_f32_e32 v254, v51, v157
	v_fmac_f32_e32 v254, v48, v154
	v_fmac_f32_e32 v254, v49, v155
	s_waitcnt lgkmcnt(4)
	v_fmac_f32_e32 v255, v50, v68
	v_fmac_f32_e32 v255, v51, v69
	v_fmac_f32_e32 v255, v48, v66
	v_fmac_f32_e32 v255, v49, v67
	s_waitcnt lgkmcnt(3)
	v_fmac_f32_e32 v252, v52, v130
	v_fmac_f32_e32 v252, v53, v131
	v_fmac_f32_e32 v252, v54, v132
	v_fmac_f32_e32 v252, v55, v133
	s_waitcnt lgkmcnt(2)
	v_fmac_f32_e32 v253, v52, v134
	v_fmac_f32_e32 v253, v53, v135
	v_fmac_f32_e32 v253, v54, v136
	v_fmac_f32_e32 v253, v55, v137
	s_waitcnt lgkmcnt(1)
	v_fmac_f32_e32 v254, v52, v138
	v_fmac_f32_e32 v254, v53, v139
	v_fmac_f32_e32 v254, v54, v140
	v_fmac_f32_e32 v254, v55, v141
	s_waitcnt lgkmcnt(0)
	v_fmac_f32_e32 v255, v52, v142
	v_fmac_f32_e32 v255, v53, v143
	v_fmac_f32_e32 v255, v54, v144
	v_fmac_f32_e32 v255, v55, v145
	v_add_f32_dpp v103, v252, v252 row_mirror row_mask:0xf bank_mask:0xf bound_ctrl:1
	v_add_f32_dpp v103, v253, v253 row_mirror row_mask:0xf bank_mask:0xc bound_ctrl:1
	v_add_f32_dpp v123, v254, v254 row_mirror row_mask:0xf bank_mask:0xf bound_ctrl:1
	v_add_f32_dpp v123, v255, v255 row_mirror row_mask:0xf bank_mask:0xc bound_ctrl:1
	v_add_f32_dpp v103, v103, v103 row_half_mirror row_mask:0xf bank_mask:0xf bound_ctrl:1
	s_nop 0
	v_add_f32_dpp v103, v123, v123 row_half_mirror row_mask:0xf bank_mask:0xa bound_ctrl:1
	s_nop 1
	v_add_f32_dpp v103, v103, v103 quad_perm:[1,0,3,2] row_mask:0xf bank_mask:0xf bound_ctrl:1
	s_nop 1
	v_add_f32_dpp v103, v103, v103 quad_perm:[2,3,0,1] row_mask:0xf bank_mask:0xf bound_ctrl:1
	s_nop 0
	v_readlane_b32 s34, v103, 0
	v_readlane_b32 s36, v103, 16
	v_readlane_b32 s35, v103, 32
	v_readlane_b32 s37, v103, 48
	v_readlane_b32 s29, v103, 8
	v_readlane_b32 s31, v103, 24
	v_readlane_b32 s30, v103, 40
	v_readlane_b32 s33, v103, 56
	v_readlane_b32 s25, v103, 4
	v_readlane_b32 s28, v103, 20
	v_readlane_b32 s50, v103, 36
	v_readlane_b32 s51, v103, 52
	v_readlane_b32 s42, v103, 12
	v_readlane_b32 s44, v103, 28
	v_readlane_b32 s43, v103, 44
	v_readlane_b32 s45, v103, 60

.LBB0_1676:
	s_add_i32 s21, s19, 1
	s_waitcnt vmcnt(0)
	v_mov_b64_e32 v[38:39], v[84:85]
	v_mov_b64_e32 v[32:33], v[92:93]
	v_mov_b64_e32 v[34:35], v[90:91]
	v_mov_b64_e32 v[36:37], v[88:89]
	v_mov_b32_e32 v0, s21
	v_min_u32_e32 v0, 15, v0
	v_mov_b32_e32 v1, 0
	v_lshl_add_u64 v[0:1], v[82:83], 0, v[0:1]
	v_lshlrev_b64 v[2:3], 12, v[0:1]
	v_lshlrev_b64 v[0:1], 11, v[0:1]
	v_lshl_add_u64 v[12:13], v[62:63], 0, v[2:3]
	v_lshl_add_u64 v[92:93], v[64:65], 0, v[0:1]
	global_load_dwordx4 v[0:3], v[12:13], off nt
	global_load_dwordx2 v[84:85], v[92:93], off nt
	global_load_dwordx4 v[4:7], v[12:13], off offset:1024 nt
	global_load_dwordx2 v[88:89], v[92:93], off offset:512 nt
	global_load_dwordx4 v[8:11], v[12:13], off offset:2048 nt
	global_load_dwordx2 v[90:91], v[92:93], off offset:1024 nt
	s_nop 0
	global_load_dwordx4 v[12:15], v[12:13], off offset:3072 nt
	s_nop 0
	global_load_dwordx2 v[92:93], v[92:93], off offset:1536 nt
	v_lshlrev_b32_e32 v40, 16, v38
	v_and_b32_e32 v41, 0xffff0000, v38
	v_lshlrev_b32_e32 v38, 16, v39
	v_and_b32_e32 v39, 0xffff0000, v39
	v_lshlrev_b32_e32 v54, 16, v36
	v_and_b32_e32 v55, 0xffff0000, v36
	v_lshlrev_b32_e32 v94, 16, v37
	v_and_b32_e32 v95, 0xffff0000, v37
	v_lshlrev_b32_e32 v96, 16, v34
	v_and_b32_e32 v97, 0xffff0000, v34
	v_lshlrev_b32_e32 v100, 16, v35
	v_and_b32_e32 v101, 0xffff0000, v35
	v_lshlrev_b32_e32 v102, 16, v32
	v_and_b32_e32 v103, 0xffff0000, v32
	v_lshlrev_b32_e32 v104, 16, v33
	v_and_b32_e32 v105, 0xffff0000, v33
	v_pk_fma_f32 v[106:107], v[30:31], s[20:21], v[38:39] op_sel_hi:[1,0,1]
	ds_read_b128 v[30:33], v234
	ds_read_b128 v[34:37], v234 offset:4096
	v_pk_fma_f32 v[28:29], v[28:29], s[20:21], v[40:41] op_sel_hi:[1,0,1]
	v_pk_fma_f32 v[20:21], v[20:21], s[20:21], v[54:55] op_sel_hi:[1,0,1]
	v_add_f32_e32 v38, v28, v29
	v_add_f32_e32 v38, v38, v106
	v_pk_fma_f32 v[22:23], v[22:23], s[20:21], v[94:95] op_sel_hi:[1,0,1]
	v_add_f32_e32 v54, v20, v21
	v_pk_fma_f32 v[24:25], v[24:25], s[20:21], v[96:97] op_sel_hi:[1,0,1]
	v_add_f32_e32 v38, v107, v38
	v_add_f32_e32 v54, v54, v22
	v_pk_fma_f32 v[26:27], v[26:27], s[20:21], v[100:101] op_sel_hi:[1,0,1]
	v_add_f32_e32 v55, v24, v25
	v_add_f32_e32 v98, 0, v38
	v_add_f32_e32 v54, v23, v54
	v_add_f32_e32 v55, v55, v26
	v_add_f32_e32 v54, v98, v54
	v_add_f32_e32 v55, v27, v55
	v_pk_fma_f32 v[16:17], v[16:17], s[20:21], v[102:103] op_sel_hi:[1,0,1]
	v_add_f32_e32 v54, v54, v55
	v_pk_fma_f32 v[18:19], v[18:19], s[20:21], v[104:105] op_sel_hi:[1,0,1]
	v_add_f32_e32 v55, v16, v17
	v_add_f32_e32 v55, v55, v18
	v_add_f32_e32 v55, v19, v55
	v_add_f32_e32 v54, v54, v55
	s_nop 1
	v_add_f32_dpp v54, v54, v54 quad_perm:[1,0,3,2] row_mask:0xf bank_mask:0xf bound_ctrl:1
	s_nop 1
	v_add_f32_dpp v54, v54, v54 quad_perm:[2,3,0,1] row_mask:0xf bank_mask:0xf bound_ctrl:1
	s_nop 1
	v_add_f32_dpp v54, v54, v54 row_half_mirror row_mask:0xf bank_mask:0xf bound_ctrl:1
	s_nop 1
	v_add_f32_dpp v54, v54, v54 row_mirror row_mask:0xf bank_mask:0xf bound_ctrl:1
	s_nop 0
	v_readlane_b32 s2, v54, 16
	v_readlane_b32 s10, v54, 48
	v_readlane_b32 s0, v54, 0
	v_readlane_b32 s1, v54, 32
	v_mov_b32_e32 v54, s2
	v_mov_b32_e32 v55, s10
	v_pk_add_f32 v[54:55], s[0:1], v[54:55]
	s_nop 0
	v_add_f32_e32 v54, v54, v55
	v_mul_f32_e32 v54, 0x3a800000, v54
	v_pk_add_f32 v[28:29], v[28:29], v[54:55] op_sel_hi:[1,0] neg_lo:[0,1] neg_hi:[0,1]
	v_pk_add_f32 v[126:127], v[106:107], v[54:55] op_sel_hi:[1,0] neg_lo:[0,1] neg_hi:[0,1]
	v_pk_mul_f32 v[104:105], v[28:29], v[28:29]
	v_pk_mul_f32 v[106:107], v[126:127], v[126:127]
	v_pk_add_f32 v[158:159], v[20:21], v[54:55] op_sel_hi:[1,0] neg_lo:[0,1] neg_hi:[0,1]
	v_pk_add_f32 v[160:161], v[22:23], v[54:55] op_sel_hi:[1,0] neg_lo:[0,1] neg_hi:[0,1]
	v_pk_add_f32 v[100:101], v[24:25], v[54:55] op_sel_hi:[1,0] neg_lo:[0,1] neg_hi:[0,1]
	v_pk_add_f32 v[102:103], v[26:27], v[54:55] op_sel_hi:[1,0] neg_lo:[0,1] neg_hi:[0,1]
	v_pk_add_f32 v[94:95], v[16:17], v[54:55] op_sel_hi:[1,0] neg_lo:[0,1] neg_hi:[0,1]
	v_pk_add_f32 v[96:97], v[18:19], v[54:55] op_sel_hi:[1,0] neg_lo:[0,1] neg_hi:[0,1]
	v_add_f32_e32 v54, v104, v105
	v_add_f32_e32 v54, v106, v54
	v_pk_mul_f32 v[20:21], v[158:159], v[158:159]
	v_add_f32_e32 v54, v107, v54
	v_add_f32_e32 v20, v20, v54
	v_pk_mul_f32 v[22:23], v[160:161], v[160:161]
	v_add_f32_e32 v20, v21, v20
	v_add_f32_e32 v20, v22, v20
	v_pk_mul_f32 v[24:25], v[100:101], v[100:101]
	v_add_f32_e32 v20, v23, v20
	v_add_f32_e32 v20, v24, v20
	v_pk_mul_f32 v[26:27], v[102:103], v[102:103]
	v_add_f32_e32 v20, v25, v20
	v_add_f32_e32 v20, v26, v20
	v_pk_mul_f32 v[16:17], v[94:95], v[94:95]
	v_add_f32_e32 v20, v27, v20
	v_add_f32_e32 v16, v16, v20
	v_pk_mul_f32 v[18:19], v[96:97], v[96:97]
	v_add_f32_e32 v16, v17, v16
	v_add_f32_e32 v16, v18, v16
	v_add_f32_e32 v16, v19, v16
	s_nop 1
	v_add_f32_dpp v16, v16, v16 quad_perm:[1,0,3,2] row_mask:0xf bank_mask:0xf bound_ctrl:1
	s_nop 1
	v_add_f32_dpp v16, v16, v16 quad_perm:[2,3,0,1] row_mask:0xf bank_mask:0xf bound_ctrl:1
	s_nop 1
	v_add_f32_dpp v16, v16, v16 row_half_mirror row_mask:0xf bank_mask:0xf bound_ctrl:1
	s_nop 1
	v_add_f32_dpp v16, v16, v16 row_mirror row_mask:0xf bank_mask:0xf bound_ctrl:1
	s_nop 0
	v_readlane_b32 s2, v16, 16
	v_readlane_b32 s10, v16, 48
	v_readlane_b32 s0, v16, 0
	v_readlane_b32 s1, v16, 32
	v_mov_b32_e32 v16, s2
	v_mov_b32_e32 v17, s10
	v_pk_add_f32 v[16:17], s[0:1], v[16:17]
	s_mov_b32 s0, 0x800000
	v_add_f32_e32 v16, v16, v17
	v_fmamk_f32 v16, v16, 0x3a800000, v116
	v_cmp_gt_f32_e32 vcc, s0, v16
	v_mul_f32_e32 v17, 0x4b800000, v16
	s_nop 0
	v_cndmask_b32_e32 v16, v16, v17, vcc
	v_rsq_f32_e32 v54, v16
	s_nop 0
	v_mul_f32_e32 v55, 0x45800000, v54
	v_cndmask_b32_e32 v98, v54, v55, vcc
	v_pk_mul_f32 v[28:29], v[28:29], v[98:99] op_sel_hi:[1,0]
	s_waitcnt lgkmcnt(0)
	v_pk_fma_f32 v[106:107], v[30:31], v[28:29], v[34:35]
	v_pk_mul_f32 v[28:29], v[126:127], v[98:99] op_sel_hi:[1,0]
	v_pk_fma_f32 v[104:105], v[32:33], v[28:29], v[36:37]
	v_cvt_pk_bf16_f32 v28, v106, v107
	v_cvt_pk_bf16_f32 v29, v104, v105
	v_mul_f32_e32 v252, v106, v183
	v_mul_f32_e32 v253, v106, v184
	v_mul_f32_e32 v254, v106, v182
	v_mul_f32_e32 v255, v106, v185
	v_fmac_f32_e32 v252, v107, v187
	v_fmac_f32_e32 v253, v107, v188
	v_fmac_f32_e32 v254, v107, v186
	v_fmac_f32_e32 v255, v107, v189
	v_fmac_f32_e32 v252, v104, v191
	v_fmac_f32_e32 v253, v104, v192
	v_fmac_f32_e32 v254, v104, v190
	v_fmac_f32_e32 v255, v104, v193
	v_fmac_f32_e32 v252, v105, v195
	v_fmac_f32_e32 v253, v105, v196
	v_fmac_f32_e32 v254, v105, v194
	v_fmac_f32_e32 v255, v105, v197
	global_store_dwordx2 v[86:87], v[28:29], off offset:-1024
	ds_read_b128 v[32:35], v234 offset:1024
	ds_read_b128 v[36:39], v234 offset:5120
	v_pk_mul_f32 v[40:41], v[158:159], v[98:99] op_sel_hi:[1,0]
	s_waitcnt lgkmcnt(0)
	v_pk_fma_f32 v[108:109], v[40:41], v[32:33], v[36:37]
	v_pk_mul_f32 v[32:33], v[160:161], v[98:99] op_sel_hi:[1,0]
	v_pk_fma_f32 v[110:111], v[32:33], v[34:35], v[38:39]
	v_cvt_pk_bf16_f32 v32, v108, v109
	v_cvt_pk_bf16_f32 v33, v110, v111
	v_fmac_f32_e32 v252, v108, v199
	v_fmac_f32_e32 v253, v108, v200
	v_fmac_f32_e32 v254, v108, v198
	v_fmac_f32_e32 v255, v108, v201
	v_fmac_f32_e32 v252, v109, v203
	v_fmac_f32_e32 v253, v109, v204
	v_fmac_f32_e32 v254, v109, v202
	v_fmac_f32_e32 v255, v109, v205
	v_fmac_f32_e32 v252, v110, v207
	v_fmac_f32_e32 v253, v110, v208
	v_fmac_f32_e32 v254, v110, v206
	v_fmac_f32_e32 v255, v110, v209
	v_fmac_f32_e32 v252, v111, v211
	v_fmac_f32_e32 v253, v111, v212
	v_fmac_f32_e32 v254, v111, v210
	v_fmac_f32_e32 v255, v111, v213
	global_store_dwordx2 v[86:87], v[32:33], off offset:-512
	ds_read_b128 v[48:51], v234 offset:2048
	ds_read_b128 v[52:55], v234 offset:6144
	v_pk_mul_f32 v[20:21], v[102:103], v[98:99] op_sel_hi:[1,0]
	s_waitcnt lgkmcnt(0)
	v_pk_fma_f32 v[50:51], v[20:21], v[50:51], v[54:55]
	v_pk_mul_f32 v[16:17], v[100:101], v[98:99] op_sel_hi:[1,0]
	v_cvt_pk_bf16_f32 v21, v50, v51
	v_pk_fma_f32 v[48:49], v[16:17], v[48:49], v[52:53]
	v_cvt_pk_bf16_f32 v20, v48, v49
	v_fmac_f32_e32 v252, v50, v223
	v_fmac_f32_e32 v253, v50, v224
	v_fmac_f32_e32 v254, v50, v222
	v_fmac_f32_e32 v255, v50, v225
	v_fmac_f32_e32 v252, v51, v227
	v_fmac_f32_e32 v253, v51, v228
	v_fmac_f32_e32 v254, v51, v226
	v_fmac_f32_e32 v255, v51, v229
	v_fmac_f32_e32 v252, v48, v215
	v_fmac_f32_e32 v253, v48, v216
	v_fmac_f32_e32 v254, v48, v214
	v_fmac_f32_e32 v255, v48, v217
	v_fmac_f32_e32 v252, v49, v219
	v_fmac_f32_e32 v253, v49, v220
	v_fmac_f32_e32 v254, v49, v218
	v_fmac_f32_e32 v255, v49, v221
	global_store_dwordx2 v[86:87], v[20:21], off
	v_pk_mul_f32 v[46:47], v[94:95], v[98:99] op_sel_hi:[1,0]
	ds_read_b128 v[32:35], v234 offset:3072
	ds_read_b128 v[36:39], v234 offset:7168
	s_waitcnt lgkmcnt(0)
	v_pk_fma_f32 v[52:53], v[46:47], v[32:33], v[36:37]
	v_pk_mul_f32 v[32:33], v[96:97], v[98:99] op_sel_hi:[1,0]
	v_pk_fma_f32 v[54:55], v[32:33], v[34:35], v[38:39]
	v_cvt_pk_bf16_f32 v32, v52, v53
	v_cvt_pk_bf16_f32 v33, v54, v55
	v_fmac_f32_e32 v252, v52, v231
	v_fmac_f32_e32 v253, v52, v232
	v_fmac_f32_e32 v254, v52, v230
	v_fmac_f32_e32 v255, v52, v233
	v_fmac_f32_e32 v252, v53, v239
	v_fmac_f32_e32 v253, v53, v240
	v_fmac_f32_e32 v254, v53, v238
	v_fmac_f32_e32 v255, v53, v241
	v_fmac_f32_e32 v252, v54, v243
	v_fmac_f32_e32 v253, v54, v244
	v_fmac_f32_e32 v254, v54, v242
	v_fmac_f32_e32 v255, v54, v245
	v_fmac_f32_e32 v252, v55, v247
	v_fmac_f32_e32 v253, v55, v248
	v_fmac_f32_e32 v254, v55, v246
	v_fmac_f32_e32 v255, v55, v249
	global_store_dwordx2 v[86:87], v[32:33], off offset:512
	v_add_f32_dpp v250, v252, v252 row_mirror row_mask:0xf bank_mask:0xf bound_ctrl:1
	v_add_f32_dpp v250, v253, v253 row_mirror row_mask:0xf bank_mask:0xc bound_ctrl:1
	v_add_f32_dpp v251, v254, v254 row_mirror row_mask:0xf bank_mask:0xf bound_ctrl:1
	v_add_f32_dpp v251, v255, v255 row_mirror row_mask:0xf bank_mask:0xc bound_ctrl:1
	v_add_f32_dpp v250, v250, v250 row_half_mirror row_mask:0xf bank_mask:0xf bound_ctrl:1
	s_nop 0
	v_add_f32_dpp v250, v251, v251 row_half_mirror row_mask:0xf bank_mask:0xa bound_ctrl:1
	s_nop 1
	v_add_f32_dpp v250, v250, v250 quad_perm:[1,0,3,2] row_mask:0xf bank_mask:0xf bound_ctrl:1
	s_nop 1
	v_add_f32_dpp v250, v250, v250 quad_perm:[2,3,0,1] row_mask:0xf bank_mask:0xf bound_ctrl:1
	s_nop 0
	v_readlane_b32 s2, v250, 20
	v_readlane_b32 s10, v250, 52
	v_readlane_b32 s0, v250, 4
	v_readlane_b32 s1, v250, 36
	v_mov_b32_e32 v16, s2
	v_mov_b32_e32 v17, s10
	v_readlane_b32 s2, v250, 16
	v_readlane_b32 s10, v250, 48
	v_pk_add_f32 v[16:17], s[0:1], v[16:17]
	v_readlane_b32 s0, v250, 0
	v_readlane_b32 s1, v250, 32
	v_mov_b32_e32 v18, s2
	v_mov_b32_e32 v19, s10
	v_readlane_b32 s2, v250, 24
	v_readlane_b32 s10, v250, 56
	v_pk_add_f32 v[18:19], s[0:1], v[18:19]
	v_readlane_b32 s0, v250, 8
	v_readlane_b32 s1, v250, 40
	v_mov_b32_e32 v20, s2
	v_mov_b32_e32 v21, s10
	v_pk_add_f32 v[20:21], s[0:1], v[20:21]
	v_mov_b32_e32 v25, v18
	v_add_f32_e32 v26, v20, v21
	v_mov_b32_e32 v18, v17
	v_readlane_b32 s2, v250, 28
	v_readlane_b32 s10, v250, 60
	v_readlane_b32 s0, v250, 12
	v_readlane_b32 s1, v250, 44
	v_mov_b32_e32 v20, s2
	v_mov_b32_e32 v21, s10
	v_pk_add_f32 v[20:21], s[0:1], v[20:21]
	v_add_f32_e32 v27, v20, v21
	v_mov_b32_e32 v24, v16
	v_pk_add_f32 v[16:17], v[24:25], v[18:19]
	v_mov_b32_e32 v20, v178
	v_mov_b32_e32 v21, v179
	v_mov_b32_e32 v22, v180
	v_mov_b32_e32 v23, v181
	v_add_f32_e32 v19, v26, v22
	v_pk_add_f32 v[16:17], v[16:17], v[20:21]
	v_add_f32_e32 v18, v27, v23
	v_cmp_gt_f32_e32 vcc, v17, v16
	s_nop 0
	s_nop 0
	v_cndmask_b32_e32 v20, v16, v17, vcc
	v_cmp_gt_f32_e64 s[12:13], v19, v20
	v_cndmask_b32_e64 v21, 0, 1, vcc
	s_and_b64 s[10:11], s[12:13], exec
	v_cndmask_b32_e64 v20, v20, v19, s[12:13]
	v_cmp_ngt_f32_e64 s[0:1], v18, v20
	v_readfirstlane_b32 s2, v21
	s_cselect_b32 s2, 2, s2
	s_and_b64 s[10:11], s[0:1], exec
	s_cselect_b32 s2, s2, 3
	s_cmp_eq_u32 s2, 0
	s_waitcnt lgkmcnt(0)
	s_cbranch_scc0 .Lmy_rselb_1
	ds_read_b128 v[146:149], v60
	ds_read_b128 v[150:153], v60 offset:4096
	ds_read_b128 v[154:157], v60 offset:8192
	ds_read_b128 v[66:69], v60 offset:12288
	ds_read_b128 v[130:133], v60 offset:1024
	ds_read_b128 v[134:137], v60 offset:5120
	ds_read_b128 v[138:141], v60 offset:9216
	ds_read_b128 v[142:145], v60 offset:13312
	s_waitcnt lgkmcnt(7)
	v_mul_f32_e32 v252, v106, v146
	v_fmac_f32_e32 v252, v107, v147
	v_fmac_f32_e32 v252, v104, v148
	v_fmac_f32_e32 v252, v105, v149
	s_waitcnt lgkmcnt(6)
	v_mul_f32_e32 v253, v106, v150
	v_fmac_f32_e32 v253, v107, v151
	v_fmac_f32_e32 v253, v104, v152
	v_fmac_f32_e32 v253, v105, v153
	s_waitcnt lgkmcnt(5)
	v_mul_f32_e32 v254, v106, v154
	v_fmac_f32_e32 v254, v107, v155
	v_fmac_f32_e32 v254, v104, v156
	v_fmac_f32_e32 v254, v105, v157
	s_waitcnt lgkmcnt(4)
	v_mul_f32_e32 v255, v106, v66
	v_fmac_f32_e32 v255, v107, v67
	v_fmac_f32_e32 v255, v104, v68
	v_fmac_f32_e32 v255, v105, v69
	ds_read_b128 v[146:149], v60 offset:2048
	ds_read_b128 v[150:153], v60 offset:6144
	ds_read_b128 v[154:157], v60 offset:10240
	ds_read_b128 v[66:69], v60 offset:14336
	s_waitcnt lgkmcnt(7)
	v_fmac_f32_e32 v252, v108, v130
	v_fmac_f32_e32 v252, v109, v131
	v_fmac_f32_e32 v252, v110, v132
	v_fmac_f32_e32 v252, v111, v133
	s_waitcnt lgkmcnt(6)
	v_fmac_f32_e32 v253, v108, v134
	v_fmac_f32_e32 v253, v109, v135
	v_fmac_f32_e32 v253, v110, v136
	v_fmac_f32_e32 v253, v111, v137
	s_waitcnt lgkmcnt(5)
	v_fmac_f32_e32 v254, v108, v138
	v_fmac_f32_e32 v254, v109, v139
	v_fmac_f32_e32 v254, v110, v140
	v_fmac_f32_e32 v254, v111, v141
	s_waitcnt lgkmcnt(4)
	v_fmac_f32_e32 v255, v108, v142
	v_fmac_f32_e32 v255, v109, v143
	v_fmac_f32_e32 v255, v110, v144
	v_fmac_f32_e32 v255, v111, v145
	ds_read_b128 v[130:133], v60 offset:3072
	ds_read_b128 v[134:137], v60 offset:7168
	ds_read_b128 v[138:141], v60 offset:11264
	ds_read_b128 v[142:145], v60 offset:15360
	s_waitcnt lgkmcnt(7)
	v_fmac_f32_e32 v252, v50, v148
	v_fmac_f32_e32 v252, v51, v149
	v_fmac_f32_e32 v252, v48, v146
	v_fmac_f32_e32 v252, v49, v147
	s_waitcnt lgkmcnt(6)
	v_fmac_f32_e32 v253, v50, v152
	v_fmac_f32_e32 v253, v51, v153
	v_fmac_f32_e32 v253, v48, v150
	v_fmac_f32_e32 v253, v49, v151
	s_waitcnt lgkmcnt(5)
	v_fmac_f32_e32 v254, v50, v156
	v_fmac_f32_e32 v254, v51, v157
	v_fmac_f32_e32 v254, v48, v154
	v_fmac_f32_e32 v254, v49, v155
	s_waitcnt lgkmcnt(4)
	v_fmac_f32_e32 v255, v50, v68
	v_fmac_f32_e32 v255, v51, v69
	v_fmac_f32_e32 v255, v48, v66
	v_fmac_f32_e32 v255, v49, v67
	s_waitcnt lgkmcnt(3)
	v_fmac_f32_e32 v252, v52, v130
	v_fmac_f32_e32 v252, v53, v131
	v_fmac_f32_e32 v252, v54, v132
	v_fmac_f32_e32 v252, v55, v133
	s_waitcnt lgkmcnt(2)
	v_fmac_f32_e32 v253, v52, v134
	v_fmac_f32_e32 v253, v53, v135
	v_fmac_f32_e32 v253, v54, v136
	v_fmac_f32_e32 v253, v55, v137
	s_waitcnt lgkmcnt(1)
	v_fmac_f32_e32 v254, v52, v138
	v_fmac_f32_e32 v254, v53, v139
	v_fmac_f32_e32 v254, v54, v140
	v_fmac_f32_e32 v254, v55, v141
	s_waitcnt lgkmcnt(0)
	v_fmac_f32_e32 v255, v52, v142
	v_fmac_f32_e32 v255, v53, v143
	v_fmac_f32_e32 v255, v54, v144
	v_fmac_f32_e32 v255, v55, v145
	v_add_f32_dpp v94, v252, v252 row_mirror row_mask:0xf bank_mask:0xf bound_ctrl:1
	v_add_f32_dpp v94, v253, v253 row_mirror row_mask:0xf bank_mask:0xc bound_ctrl:1
	v_add_f32_dpp v96, v254, v254 row_mirror row_mask:0xf bank_mask:0xf bound_ctrl:1
	v_add_f32_dpp v96, v255, v255 row_mirror row_mask:0xf bank_mask:0xc bound_ctrl:1
	v_add_f32_dpp v94, v94, v94 row_half_mirror row_mask:0xf bank_mask:0xf bound_ctrl:1
	s_nop 0
	v_add_f32_dpp v94, v96, v96 row_half_mirror row_mask:0xf bank_mask:0xa bound_ctrl:1
	s_nop 1
	v_add_f32_dpp v94, v94, v94 quad_perm:[1,0,3,2] row_mask:0xf bank_mask:0xf bound_ctrl:1
	s_nop 1
	v_add_f32_dpp v94, v94, v94 quad_perm:[2,3,0,1] row_mask:0xf bank_mask:0xf bound_ctrl:1
	s_nop 0
	v_readlane_b32 s14, v94, 0
	v_readlane_b32 s94, v94, 16
	v_readlane_b32 s15, v94, 32
	v_readlane_b32 s95, v94, 48
	v_readlane_b32 s87, v94, 8
	v_readlane_b32 s91, v94, 24
	v_readlane_b32 s90, v94, 40
	v_readlane_b32 s92, v94, 56
	v_readlane_b32 s65, v94, 4
	v_readlane_b32 s75, v94, 20
	v_readlane_b32 s66, v94, 36
	v_readlane_b32 s78, v94, 52
	v_readlane_b32 s51, v94, 12
	v_readlane_b32 s53, v94, 28
	v_readlane_b32 s52, v94, 44
	v_readlane_b32 s54, v94, 60
	s_branch .Lmy_rselb_end
.Lmy_rselb_1:
	s_cmp_eq_u32 s2, 1
	s_cbranch_scc0 .Lmy_rselb_2
	ds_read_b128 v[146:149], v60 offset:16384
	ds_read_b128 v[150:153], v60 offset:20480
	ds_read_b128 v[154:157], v60 offset:24576
	ds_read_b128 v[66:69], v60 offset:28672
	ds_read_b128 v[130:133], v60 offset:17408
	ds_read_b128 v[134:137], v60 offset:21504
	ds_read_b128 v[138:141], v60 offset:25600
	ds_read_b128 v[142:145], v60 offset:29696
	s_waitcnt lgkmcnt(7)
	v_mul_f32_e32 v252, v106, v146
	v_fmac_f32_e32 v252, v107, v147
	v_fmac_f32_e32 v252, v104, v148
	v_fmac_f32_e32 v252, v105, v149
	s_waitcnt lgkmcnt(6)
	v_mul_f32_e32 v253, v106, v150
	v_fmac_f32_e32 v253, v107, v151
	v_fmac_f32_e32 v253, v104, v152
	v_fmac_f32_e32 v253, v105, v153
	s_waitcnt lgkmcnt(5)
	v_mul_f32_e32 v254, v106, v154
	v_fmac_f32_e32 v254, v107, v155
	v_fmac_f32_e32 v254, v104, v156
	v_fmac_f32_e32 v254, v105, v157
	s_waitcnt lgkmcnt(4)
	v_mul_f32_e32 v255, v106, v66
	v_fmac_f32_e32 v255, v107, v67
	v_fmac_f32_e32 v255, v104, v68
	v_fmac_f32_e32 v255, v105, v69
	ds_read_b128 v[146:149], v60 offset:18432
	ds_read_b128 v[150:153], v60 offset:22528
	ds_read_b128 v[154:157], v60 offset:26624
	ds_read_b128 v[66:69], v60 offset:30720
	s_waitcnt lgkmcnt(7)
	v_fmac_f32_e32 v252, v108, v130
	v_fmac_f32_e32 v252, v109, v131
	v_fmac_f32_e32 v252, v110, v132
	v_fmac_f32_e32 v252, v111, v133
	s_waitcnt lgkmcnt(6)
	v_fmac_f32_e32 v253, v108, v134
	v_fmac_f32_e32 v253, v109, v135
	v_fmac_f32_e32 v253, v110, v136
	v_fmac_f32_e32 v253, v111, v137
	s_waitcnt lgkmcnt(5)
	v_fmac_f32_e32 v254, v108, v138
	v_fmac_f32_e32 v254, v109, v139
	v_fmac_f32_e32 v254, v110, v140
	v_fmac_f32_e32 v254, v111, v141
	s_waitcnt lgkmcnt(4)
	v_fmac_f32_e32 v255, v108, v142
	v_fmac_f32_e32 v255, v109, v143
	v_fmac_f32_e32 v255, v110, v144
	v_fmac_f32_e32 v255, v111, v145
	ds_read_b128 v[130:133], v60 offset:19456
	ds_read_b128 v[134:137], v60 offset:23552
	ds_read_b128 v[138:141], v60 offset:27648
	ds_read_b128 v[142:145], v60 offset:31744
	s_waitcnt lgkmcnt(7)
	v_fmac_f32_e32 v252, v50, v148
	v_fmac_f32_e32 v252, v51, v149
	v_fmac_f32_e32 v252, v48, v146
	v_fmac_f32_e32 v252, v49, v147
	s_waitcnt lgkmcnt(6)
	v_fmac_f32_e32 v253, v50, v152
	v_fmac_f32_e32 v253, v51, v153
	v_fmac_f32_e32 v253, v48, v150
	v_fmac_f32_e32 v253, v49, v151
	s_waitcnt lgkmcnt(5)
	v_fmac_f32_e32 v254, v50, v156
	v_fmac_f32_e32 v254, v51, v157
	v_fmac_f32_e32 v254, v48, v154
	v_fmac_f32_e32 v254, v49, v155
	s_waitcnt lgkmcnt(4)
	v_fmac_f32_e32 v255, v50, v68
	v_fmac_f32_e32 v255, v51, v69
	v_fmac_f32_e32 v255, v48, v66
	v_fmac_f32_e32 v255, v49, v67
	s_waitcnt lgkmcnt(3)
	v_fmac_f32_e32 v252, v52, v130
	v_fmac_f32_e32 v252, v53, v131
	v_fmac_f32_e32 v252, v54, v132
	v_fmac_f32_e32 v252, v55, v133
	s_waitcnt lgkmcnt(2)
	v_fmac_f32_e32 v253, v52, v134
	v_fmac_f32_e32 v253, v53, v135
	v_fmac_f32_e32 v253, v54, v136
	v_fmac_f32_e32 v253, v55, v137
	s_waitcnt lgkmcnt(1)
	v_fmac_f32_e32 v254, v52, v138
	v_fmac_f32_e32 v254, v53, v139
	v_fmac_f32_e32 v254, v54, v140
	v_fmac_f32_e32 v254, v55, v141
	s_waitcnt lgkmcnt(0)
	v_fmac_f32_e32 v255, v52, v142
	v_fmac_f32_e32 v255, v53, v143
	v_fmac_f32_e32 v255, v54, v144
	v_fmac_f32_e32 v255, v55, v145
	v_add_f32_dpp v125, v252, v252 row_mirror row_mask:0xf bank_mask:0xf bound_ctrl:1
	v_add_f32_dpp v125, v253, v253 row_mirror row_mask:0xf bank_mask:0xc bound_ctrl:1
	v_add_f32_dpp v98, v254, v254 row_mirror row_mask:0xf bank_mask:0xf bound_ctrl:1
	v_add_f32_dpp v98, v255, v255 row_mirror row_mask:0xf bank_mask:0xc bound_ctrl:1
	v_add_f32_dpp v125, v125, v125 row_half_mirror row_mask:0xf bank_mask:0xf bound_ctrl:1
	s_nop 0
	v_add_f32_dpp v125, v98, v98 row_half_mirror row_mask:0xf bank_mask:0xa bound_ctrl:1
	s_nop 1
	v_add_f32_dpp v125, v125, v125 quad_perm:[1,0,3,2] row_mask:0xf bank_mask:0xf bound_ctrl:1
	s_nop 1
	v_add_f32_dpp v125, v125, v125 quad_perm:[2,3,0,1] row_mask:0xf bank_mask:0xf bound_ctrl:1
	s_nop 0
	v_readlane_b32 s35, v125, 0
	v_readlane_b32 s37, v125, 16
	v_readlane_b32 s36, v125, 32
	v_readlane_b32 s38, v125, 48
	v_readlane_b32 s23, v125, 8
	v_readlane_b32 s27, v125, 24
	v_readlane_b32 s26, v125, 40
	v_readlane_b32 s93, v125, 56
	v_readlane_b32 s81, v125, 4
	v_readlane_b32 s83, v125, 20
	v_readlane_b32 s82, v125, 36
	v_readlane_b32 s84, v125, 52
	v_readlane_b32 s63, v125, 12
	v_readlane_b32 s67, v125, 28
	v_readlane_b32 s64, v125, 44
	v_readlane_b32 s70, v125, 60
	s_branch .Lmy_rselb_end
.Lmy_rselb_2:
	s_cmp_eq_u32 s2, 2
	s_cbranch_scc0 .Lmy_rselb_3
	ds_read_b128 v[146:149], v60 offset:32768
	ds_read_b128 v[150:153], v60 offset:36864
	ds_read_b128 v[154:157], v60 offset:40960
	ds_read_b128 v[66:69], v60 offset:45056
	ds_read_b128 v[130:133], v60 offset:33792
	ds_read_b128 v[134:137], v60 offset:37888
	ds_read_b128 v[138:141], v60 offset:41984
	ds_read_b128 v[142:145], v60 offset:46080
	s_waitcnt lgkmcnt(7)
	v_mul_f32_e32 v252, v106, v146
	v_fmac_f32_e32 v252, v107, v147
	v_fmac_f32_e32 v252, v104, v148
	v_fmac_f32_e32 v252, v105, v149
	s_waitcnt lgkmcnt(6)
	v_mul_f32_e32 v253, v106, v150
	v_fmac_f32_e32 v253, v107, v151
	v_fmac_f32_e32 v253, v104, v152
	v_fmac_f32_e32 v253, v105, v153
	s_waitcnt lgkmcnt(5)
	v_mul_f32_e32 v254, v106, v154
	v_fmac_f32_e32 v254, v107, v155
	v_fmac_f32_e32 v254, v104, v156
	v_fmac_f32_e32 v254, v105, v157
	s_waitcnt lgkmcnt(4)
	v_mul_f32_e32 v255, v106, v66
	v_fmac_f32_e32 v255, v107, v67
	v_fmac_f32_e32 v255, v104, v68
	v_fmac_f32_e32 v255, v105, v69
	ds_read_b128 v[146:149], v60 offset:34816
	ds_read_b128 v[150:153], v60 offset:38912
	ds_read_b128 v[154:157], v60 offset:43008
	ds_read_b128 v[66:69], v60 offset:47104
	s_waitcnt lgkmcnt(7)
	v_fmac_f32_e32 v252, v108, v130
	v_fmac_f32_e32 v252, v109, v131
	v_fmac_f32_e32 v252, v110, v132
	v_fmac_f32_e32 v252, v111, v133
	s_waitcnt lgkmcnt(6)
	v_fmac_f32_e32 v253, v108, v134
	v_fmac_f32_e32 v253, v109, v135
	v_fmac_f32_e32 v253, v110, v136
	v_fmac_f32_e32 v253, v111, v137
	s_waitcnt lgkmcnt(5)
	v_fmac_f32_e32 v254, v108, v138
	v_fmac_f32_e32 v254, v109, v139
	v_fmac_f32_e32 v254, v110, v140
	v_fmac_f32_e32 v254, v111, v141
	s_waitcnt lgkmcnt(4)
	v_fmac_f32_e32 v255, v108, v142
	v_fmac_f32_e32 v255, v109, v143
	v_fmac_f32_e32 v255, v110, v144
	v_fmac_f32_e32 v255, v111, v145
	ds_read_b128 v[130:133], v60 offset:35840
	ds_read_b128 v[134:137], v60 offset:39936
	ds_read_b128 v[138:141], v60 offset:44032
	ds_read_b128 v[142:145], v60 offset:48128
	s_waitcnt lgkmcnt(7)
	v_fmac_f32_e32 v252, v50, v148
	v_fmac_f32_e32 v252, v51, v149
	v_fmac_f32_e32 v252, v48, v146
	v_fmac_f32_e32 v252, v49, v147
	s_waitcnt lgkmcnt(6)
	v_fmac_f32_e32 v253, v50, v152
	v_fmac_f32_e32 v253, v51, v153
	v_fmac_f32_e32 v253, v48, v150
	v_fmac_f32_e32 v253, v49, v151
	s_waitcnt lgkmcnt(5)
	v_fmac_f32_e32 v254, v50, v156
	v_fmac_f32_e32 v254, v51, v157
	v_fmac_f32_e32 v254, v48, v154
	v_fmac_f32_e32 v254, v49, v155
	s_waitcnt lgkmcnt(4)
	v_fmac_f32_e32 v255, v50, v68
	v_fmac_f32_e32 v255, v51, v69
	v_fmac_f32_e32 v255, v48, v66
	v_fmac_f32_e32 v255, v49, v67
	s_waitcnt lgkmcnt(3)
	v_fmac_f32_e32 v252, v52, v130
	v_fmac_f32_e32 v252, v53, v131
	v_fmac_f32_e32 v252, v54, v132
	v_fmac_f32_e32 v252, v55, v133
	s_waitcnt lgkmcnt(2)
	v_fmac_f32_e32 v253, v52, v134
	v_fmac_f32_e32 v253, v53, v135
	v_fmac_f32_e32 v253, v54, v136
	v_fmac_f32_e32 v253, v55, v137
	s_waitcnt lgkmcnt(1)
	v_fmac_f32_e32 v254, v52, v138
	v_fmac_f32_e32 v254, v53, v139
	v_fmac_f32_e32 v254, v54, v140
	v_fmac_f32_e32 v254, v55, v141
	s_waitcnt lgkmcnt(0)
	v_fmac_f32_e32 v255, v52, v142
	v_fmac_f32_e32 v255, v53, v143
	v_fmac_f32_e32 v255, v54, v144
	v_fmac_f32_e32 v255, v55, v145
	v_add_f32_dpp v111, v252, v252 row_mirror row_mask:0xf bank_mask:0xf bound_ctrl:1
	v_add_f32_dpp v111, v253, v253 row_mirror row_mask:0xf bank_mask:0xc bound_ctrl:1
	v_add_f32_dpp v109, v254, v254 row_mirror row_mask:0xf bank_mask:0xf bound_ctrl:1
	v_add_f32_dpp v109, v255, v255 row_mirror row_mask:0xf bank_mask:0xc bound_ctrl:1
	v_add_f32_dpp v111, v111, v111 row_half_mirror row_mask:0xf bank_mask:0xf bound_ctrl:1
	s_nop 0
	v_add_f32_dpp v111, v109, v109 row_half_mirror row_mask:0xf bank_mask:0xa bound_ctrl:1
	s_nop 1
	v_add_f32_dpp v111, v111, v111 quad_perm:[1,0,3,2] row_mask:0xf bank_mask:0xf bound_ctrl:1
	s_nop 1
	v_add_f32_dpp v111, v111, v111 quad_perm:[2,3,0,1] row_mask:0xf bank_mask:0xf bound_ctrl:1
	s_nop 0
	v_readlane_b32 s59, v111, 0
	v_readlane_b32 s61, v111, 16
	v_readlane_b32 s60, v111, 32
	v_readlane_b32 s62, v111, 48
	v_readlane_b32 s55, v111, 8
	v_readlane_b32 s57, v111, 24
	v_readlane_b32 s56, v111, 40
	v_readlane_b32 s58, v111, 56
	v_readlane_b32 s47, v111, 4
	v_readlane_b32 s49, v111, 20
	v_readlane_b32 s48, v111, 36
	v_readlane_b32 s50, v111, 52
	v_readlane_b32 s43, v111, 12
	v_readlane_b32 s45, v111, 28
	v_readlane_b32 s44, v111, 44
	v_readlane_b32 s46, v111, 60
	s_branch .Lmy_rselb_end
.Lmy_rselb_3:
	ds_read_b128 v[146:149], v60 offset:49152
	ds_read_b128 v[150:153], v60 offset:53248
	ds_read_b128 v[154:157], v60 offset:57344
	ds_read_b128 v[66:69], v60 offset:61440
	ds_read_b128 v[130:133], v60 offset:50176
	ds_read_b128 v[134:137], v60 offset:54272
	ds_read_b128 v[138:141], v60 offset:58368
	ds_read_b128 v[142:145], v60 offset:62464
	s_waitcnt lgkmcnt(7)
	v_mul_f32_e32 v252, v106, v146
	v_fmac_f32_e32 v252, v107, v147
	v_fmac_f32_e32 v252, v104, v148
	v_fmac_f32_e32 v252, v105, v149
	s_waitcnt lgkmcnt(6)
	v_mul_f32_e32 v253, v106, v150
	v_fmac_f32_e32 v253, v107, v151
	v_fmac_f32_e32 v253, v104, v152
	v_fmac_f32_e32 v253, v105, v153
	s_waitcnt lgkmcnt(5)
	v_mul_f32_e32 v254, v106, v154
	v_fmac_f32_e32 v254, v107, v155
	v_fmac_f32_e32 v254, v104, v156
	v_fmac_f32_e32 v254, v105, v157
	s_waitcnt lgkmcnt(4)
	v_mul_f32_e32 v255, v106, v66
	v_fmac_f32_e32 v255, v107, v67
	v_fmac_f32_e32 v255, v104, v68
	v_fmac_f32_e32 v255, v105, v69
	ds_read_b128 v[146:149], v60 offset:51200
	ds_read_b128 v[150:153], v60 offset:55296
	ds_read_b128 v[154:157], v60 offset:59392
	ds_read_b128 v[66:69], v60 offset:63488
	s_waitcnt lgkmcnt(7)
	v_fmac_f32_e32 v252, v108, v130
	v_fmac_f32_e32 v252, v109, v131
	v_fmac_f32_e32 v252, v110, v132
	v_fmac_f32_e32 v252, v111, v133
	s_waitcnt lgkmcnt(6)
	v_fmac_f32_e32 v253, v108, v134
	v_fmac_f32_e32 v253, v109, v135
	v_fmac_f32_e32 v253, v110, v136
	v_fmac_f32_e32 v253, v111, v137
	s_waitcnt lgkmcnt(5)
	v_fmac_f32_e32 v254, v108, v138
	v_fmac_f32_e32 v254, v109, v139
	v_fmac_f32_e32 v254, v110, v140
	v_fmac_f32_e32 v254, v111, v141
	s_waitcnt lgkmcnt(4)
	v_fmac_f32_e32 v255, v108, v142
	v_fmac_f32_e32 v255, v109, v143
	v_fmac_f32_e32 v255, v110, v144
	v_fmac_f32_e32 v255, v111, v145
	ds_read_b128 v[130:133], v60 offset:52224
	ds_read_b128 v[134:137], v60 offset:56320
	ds_read_b128 v[138:141], v60 offset:60416
	ds_read_b128 v[142:145], v60 offset:64512
	s_waitcnt lgkmcnt(7)
	v_fmac_f32_e32 v252, v50, v148
	v_fmac_f32_e32 v252, v51, v149
	v_fmac_f32_e32 v252, v48, v146
	v_fmac_f32_e32 v252, v49, v147
	s_waitcnt lgkmcnt(6)
	v_fmac_f32_e32 v253, v50, v152
	v_fmac_f32_e32 v253, v51, v153
	v_fmac_f32_e32 v253, v48, v150
	v_fmac_f32_e32 v253, v49, v151
	s_waitcnt lgkmcnt(5)
	v_fmac_f32_e32 v254, v50, v156
	v_fmac_f32_e32 v254, v51, v157
	v_fmac_f32_e32 v254, v48, v154
	v_fmac_f32_e32 v254, v49, v155
	s_waitcnt lgkmcnt(4)
	v_fmac_f32_e32 v255, v50, v68
	v_fmac_f32_e32 v255, v51, v69
	v_fmac_f32_e32 v255, v48, v66
	v_fmac_f32_e32 v255, v49, v67
	s_waitcnt lgkmcnt(3)
	v_fmac_f32_e32 v252, v52, v130
	v_fmac_f32_e32 v252, v53, v131
	v_fmac_f32_e32 v252, v54, v132
	v_fmac_f32_e32 v252, v55, v133
	s_waitcnt lgkmcnt(2)
	v_fmac_f32_e32 v253, v52, v134
	v_fmac_f32_e32 v253, v53, v135
	v_fmac_f32_e32 v253, v54, v136
	v_fmac_f32_e32 v253, v55, v137
	s_waitcnt lgkmcnt(1)
	v_fmac_f32_e32 v254, v52, v138
	v_fmac_f32_e32 v254, v53, v139
	v_fmac_f32_e32 v254, v54, v140
	v_fmac_f32_e32 v254, v55, v141
	s_waitcnt lgkmcnt(0)
	v_fmac_f32_e32 v255, v52, v142
	v_fmac_f32_e32 v255, v53, v143
	v_fmac_f32_e32 v255, v54, v144
	v_fmac_f32_e32 v255, v55, v145
	v_add_f32_dpp v103, v252, v252 row_mirror row_mask:0xf bank_mask:0xf bound_ctrl:1
	v_add_f32_dpp v103, v253, v253 row_mirror row_mask:0xf bank_mask:0xc bound_ctrl:1
	v_add_f32_dpp v123, v254, v254 row_mirror row_mask:0xf bank_mask:0xf bound_ctrl:1
	v_add_f32_dpp v123, v255, v255 row_mirror row_mask:0xf bank_mask:0xc bound_ctrl:1
	v_add_f32_dpp v103, v103, v103 row_half_mirror row_mask:0xf bank_mask:0xf bound_ctrl:1
	s_nop 0
	v_add_f32_dpp v103, v123, v123 row_half_mirror row_mask:0xf bank_mask:0xa bound_ctrl:1
	s_nop 1
	v_add_f32_dpp v103, v103, v103 quad_perm:[1,0,3,2] row_mask:0xf bank_mask:0xf bound_ctrl:1
	s_nop 1
	v_add_f32_dpp v103, v103, v103 quad_perm:[2,3,0,1] row_mask:0xf bank_mask:0xf bound_ctrl:1
	s_nop 0
	v_readlane_b32 s39, v103, 0
	v_readlane_b32 s41, v103, 16
	v_readlane_b32 s40, v103, 32
	v_readlane_b32 s42, v103, 48
	v_readlane_b32 s30, v103, 8
	v_readlane_b32 s33, v103, 24
	v_readlane_b32 s31, v103, 40
	v_readlane_b32 s34, v103, 56
	v_readlane_b32 s28, v103, 4
	v_readlane_b32 s29, v103, 20
	v_readlane_b32 s85, v103, 36
	v_readlane_b32 s86, v103, 52
	v_readlane_b32 s71, v103, 12
	v_readlane_b32 s79, v103, 28
	v_readlane_b32 s74, v103, 44
	v_readlane_b32 s80, v103, 60
